# latent mLSTM chain split point 32->44 chunks (balance full vs light+full halves) + P9 stagger + epilogue prefetch + C-update pipelining
# speedup vs baseline: 1.0013x; 1.0013x over previous
.LBB0_614:
	v_readlane_b32 s6, v240, 11
	s_and_b32 s8, s6, 1
	s_and_b64 s[6:7], s[4:5], exec
	v_readlane_b32 s6, v240, 20
	s_cselect_b32 s15, s53, s6
	v_readlane_b32 s6, v241, 22
	s_cselect_b32 s16, s52, s6
	s_cmp_eq_u32 s8, 0
	s_cselect_b32 s88, 44, 64
	s_mul_i32 s89, s8, 44
	s_lshl_b32 s18, s38, 1
	s_movk_i32 s19, 0x110
	s_cmp_gt_i32 s38, 3
	v_add_u32_e32 v63, 0xffffff00, v58
	v_mad_u32_u24 v88, v84, s19, 0
	s_movk_i32 s6, 0xfef2
	s_cselect_b64 s[72:73], -1, 0
	v_ashrrev_i32_e32 v63, 1, v63
	s_add_i32 s17, 0, 0x14600
	v_mad_i32_i24 v89, v84, s6, v88
	v_or_b32_e32 v90, s12, v65
	s_movk_i32 s6, 0x90
	v_lshl_add_u32 v94, v63, 2, s17
	v_lshl_add_u32 v96, v58, 2, s17
	s_add_i32 s17, 0, 0x14800
	v_mul_lo_u32 v62, v90, s6
	v_and_b32_e32 v92, 48, v58
	s_add_i32 s20, 0, 0x11800
	s_add_i32 s21, 0, 0x14900
	v_lshl_add_u32 v97, v58, 1, s17
	s_lshl_b32 s17, s14, 1
	v_and_b32_e32 v72, 1, v58
	v_add_u32_e32 v80, s20, v62
	v_add_u32_e32 v58, s20, v92
	s_add_u32 s20, s16, s17
	s_addc_u32 s15, s15, 0
	s_lshl_b64 s[16:17], s[12:13], 1
	s_add_u32 s16, s20, s16
	s_addc_u32 s17, s15, s17
	s_or_b32 s97, s18, 1
	s_lshl_b32 s94, s38, 5
	s_lshl_b32 s96, s97, 4
	v_add_u32_e32 v91, 0, v62
	v_mul_lo_u32 v73, v63, s6
	v_lshlrev_b32_e32 v62, 1, v65
	v_mov_b32_e32 v63, v61
	s_add_u32 s74, s12, s14
	v_lshl_add_u64 v[74:75], s[16:17], 0, v[62:63]
	v_mul_lo_u32 v62, v59, s19
	s_addc_u32 s75, s13, 0
	v_add_u32_e32 v82, 0, v62
	v_mul_lo_u32 v62, v70, s19
	s_cmp_gt_i32 s38, -1
	v_add_u32_e32 v83, 0, v62
	v_lshlrev_b32_e32 v62, 1, v71
	s_cselect_b64 s[76:77], -1, 0
	s_cmp_gt_i32 s38, 0
	v_lshlrev_b32_e32 v66, 3, v66
	v_lshl_add_u64 v[76:77], s[0:1], 0, v[62:63]
	s_cselect_b64 s[78:79], -1, 0
	v_or_b32_e32 v63, 17, v79
	v_cmp_gt_i32_e64 s[22:23], v67, v90
	s_cmp_gt_i32 s38, 1
	v_or_b32_e32 v67, 33, v79
	v_or_b32_e32 v71, 49, v79
	v_add_u32_e32 v73, 0, v73
	v_lshlrev_b32_e32 v78, 6, v72
	v_cmp_eq_u32_e64 s[6:7], 0, v72
	v_lshl_add_u32 v72, v90, 7, v91
	v_cmp_eq_u32_e64 s[8:9], 0, v65
	v_lshl_add_u32 v95, v90, 2, s21
	v_add_u32_e32 v81, 0, v66
	v_lshl_add_u32 v98, v79, 2, s21
	v_mul_u32_u24_e32 v99, 0x90, v65
	s_mul_i32 s95, s38, 0x900
	v_mul_u32_u24_e32 v100, 0x110, v65
	v_or_b32_e32 v61, 3, v79
	v_or_b32_e32 v62, 2, v79
	v_cmp_gt_i32_e64 s[20:21], v63, v90
	v_or_b32_e32 v63, 19, v79
	v_or_b32_e32 v65, 18, v79
	s_cselect_b64 s[80:81], -1, 0
	v_cmp_gt_i32_e64 s[28:29], v67, v90
	v_cmp_gt_i32_e64 s[30:31], v68, v90
	v_or_b32_e32 v67, 35, v79
	v_or_b32_e32 v68, 34, v79
	s_cmp_lg_u32 s38, 3
	v_cmp_gt_i32_e64 s[38:39], v71, v90
	v_cmp_gt_i32_e64 s[40:41], v69, v90
	v_or_b32_e32 v69, 51, v79
	v_or_b32_e32 v71, 50, v79
	v_add_u32_e32 v93, 0, v92
	v_cmp_gt_u32_e64 s[10:11], 16, v84
	s_mulk_i32 s97, 0x480
	v_cmp_lt_i32_e64 s[12:13], v90, v79
	v_cmp_lt_i32_e64 s[14:15], v79, v90
	v_cmp_gt_i32_e64 s[16:17], v61, v90
	v_cmp_gt_i32_e64 s[18:19], v62, v90
	v_cmp_gt_i32_e64 s[24:25], v63, v90
	v_cmp_gt_i32_e64 s[26:27], v65, v90
	v_cmp_gt_i32_e64 s[34:35], v67, v90
	v_cmp_gt_i32_e64 s[36:37], v68, v90
	s_cselect_b64 s[82:83], -1, 0
	v_cmp_gt_i32_e64 s[42:43], v69, v90
	v_cmp_gt_i32_e64 s[44:45], v71, v90
	v_xor_b32_e32 v101, 0x2fff, v69
	v_xor_b32_e32 v102, 0x2fff, v71
	v_sub_u32_e32 v103, 0, v79
	v_xor_b32_e32 v104, 0x2fff, v67
	v_xor_b32_e32 v105, 0x2fff, v68
	v_xor_b32_e32 v106, 0x2fff, v63
	v_xor_b32_e32 v107, 0x2fff, v65
	v_xor_b32_e32 v108, 0x2fff, v61
	v_xor_b32_e32 v109, 0x2fff, v62
	v_or_b32_e32 v110, 0x2000, v69
	v_or_b32_e32 v111, 0x2000, v71
	v_or_b32_e32 v112, 0x2000, v67
	v_or_b32_e32 v113, 0x2000, v68
	v_or_b32_e32 v114, 0x2000, v63
	v_or_b32_e32 v115, 0x2000, v65
	v_or_b32_e32 v116, 0x2000, v61
	v_or_b32_e32 v117, 0x2000, v62
	v_sub_u32_e32 v118, 0x2fbf, v70
	v_sub_u32_e32 v119, 0x2fbf, v59
	v_or_b32_e32 v120, 0x2040, v84
	v_xor_b32_e32 v121, 0x2fbf, v84
	v_add_u32_e32 v122, 0x2040, v70
	v_add_u32_e32 v123, 0x2040, v59
	v_add_u32_e32 v124, v82, v60
	v_add_u32_e32 v125, v83, v60
	v_add_u32_e32 v126, v73, v78
	v_add_u32_e32 v127, v72, v92
	v_add_u32_e32 v128, v81, v100
	v_add_u32_e32 v129, v58, v99
	v_mbcnt_hi_u32_b32 v133, -1, v131
	v_add_u32_e32 v135, v80, v66
	v_mov_b32_e32 v136, v79
	s_branch .LBB0_616

.LBB0_1199:
	s_or_b64 exec, exec, s[0:1]
	v_mov_b32_e32 v12, v1
	s_waitcnt lgkmcnt(0)
	s_barrier
	s_cmpk_lt_i32 s79, 0x80
	s_cbranch_scc1 .Lp9_nostagger
	s_sleep 127
	s_sleep 127
	s_sleep 127
	s_sleep 127
	s_sleep 127
	s_sleep 127
	s_sleep 127
.Lp9_nostagger:
	s_cmpk_gt_i32 s79, 0x107f
	v_readfirstlane_b32 s1, v12
	s_cbranch_scc1 .LBB0_1215
	v_lshlrev_b32_e32 v2, 4, v12
	v_add_u32_e32 v3, 0x2000, v2
	v_ashrrev_i32_e32 v4, 31, v3
	v_lshrrev_b32_e32 v4, 22, v4
	v_add_u32_e32 v4, v3, v4
	v_ashrrev_i32_e32 v10, 10, v4
	v_mul_i32_i24_e32 v4, 0x400, v10
	v_sub_u32_e32 v3, v3, v4
	v_lshrrev_b32_e32 v4, 4, v3
	v_bitop3_b32 v3, v4, v3, 32 bitop3:0x6c
	v_ashrrev_i32_e32 v4, 31, v3
	v_lshrrev_b32_e32 v4, 26, v4
	v_add_u32_e32 v4, v3, v4
	v_lshlrev_b32_e32 v5, 3, v10
	v_ashrrev_i32_e32 v11, 6, v4
	v_and_b32_e32 v5, -16, v5
	v_add_u32_e32 v5, v11, v5
	v_and_b32_e32 v6, 3, v11
	s_mov_b32 s0, 0xfffe0
	v_lshrrev_b32_e32 v7, 2, v5
	v_lshlrev_b32_e32 v8, 1, v5
	v_and_b32_e32 v4, 0xc0, v4
	v_and_or_b32 v6, v5, s0, v6
	v_and_b32_e32 v7, 4, v7
	v_and_b32_e32 v8, 24, v8
	v_sub_u32_e32 v3, v3, v4
	v_mov_b32_e32 v4, 1
	v_or3_b32 v6, v6, v7, v8
	v_lshlrev_b32_e32 v7, 5, v10
	v_ashrrev_i16_sdwa v3, v4, sext(v3) dst_sel:DWORD dst_unused:UNUSED_PAD src0_sel:DWORD src1_sel:BYTE_0
	v_and_b32_e32 v7, 32, v7
	v_bfe_i32 v13, v3, 0, 16
	v_add_lshl_u32 v3, v7, v13, 1
	v_lshl_add_u32 v148, v6, 12, v3
	v_lshl_add_u32 v150, v5, 12, v3
	v_bfe_i32 v3, v12, 27, 1
	v_lshrrev_b32_e32 v3, 22, v3
	v_add_u32_e32 v3, v2, v3
	v_and_b32_e32 v3, 0xfffffc00, v3
	v_sub_u32_e32 v2, v2, v3
	v_lshrrev_b32_e32 v3, 4, v2
	v_ashrrev_i32_e32 v5, 31, v12
	v_bitop3_b32 v2, v3, v2, 32 bitop3:0x6c
	v_lshrrev_b32_e32 v5, 26, v5
	v_ashrrev_i32_e32 v3, 31, v2
	v_add_u32_e32 v5, v12, v5
	v_lshrrev_b32_e32 v3, 26, v3
	s_waitcnt vmcnt(50)
	v_ashrrev_i32_e32 v15, 6, v5
	v_add_u32_e32 v3, v2, v3
	v_lshlrev_b32_e32 v5, 3, v15
	v_ashrrev_i32_e32 v14, 6, v3
	v_and_b32_e32 v5, -16, v5
	v_add_u32_e32 v5, v14, v5
	v_and_b32_e32 v6, 3, v14
	s_ashr_i32 s34, s79, 31
	v_and_or_b32 v6, v5, s0, v6
	s_lshr_b32 s0, s34, 29
	s_add_i32 s0, s79, s0
	s_ashr_i32 s8, s1, 6
	s_ashr_i32 s2, s0, 3
	s_and_b32 s0, s0, -8
	s_ashr_i32 s16, s1, 8
	s_lshl_b32 s33, s8, 10
	s_sub_i32 s0, s79, s0
	s_cmp_lt_i32 s0, 0
	s_movk_i32 s35, 0x211
	s_cselect_b32 s3, s35, 0x210
	s_mul_i32 s0, s0, s3
	s_add_i32 s0, s0, s2
	s_mul_hi_i32 s2, s0, 0x2e8ba2e9
	s_lshr_b32 s3, s2, 31
	s_ashr_i32 s2, s2, 6
	s_add_i32 s2, s2, s3
	s_lshl_b32 s3, s2, 3
	s_mulk_i32 s2, 0x160
	s_sub_i32 s2, s0, s2
	s_sext_i32_i16 s0, s2
	s_bfe_u32 s0, s0, 0x3001c
	s_add_i32 s6, s2, s0
	s_sext_i32_i16 s0, s6
	s_and_b32 s6, s6, 0xfff8
	s_sub_i32 s2, s2, s6
	s_sext_i32_i16 s2, s2
	v_lshrrev_b32_e32 v7, 2, v5
	v_lshlrev_b32_e32 v8, 1, v5
	v_and_b32_e32 v3, 0xc0, v3
	s_lshr_b32 s0, s0, 3
	s_add_i32 s6, s3, s2
	v_and_b32_e32 v7, 4, v7
	v_and_b32_e32 v8, 24, v8
	v_sub_u32_e32 v2, v2, v3
	s_ashr_i32 s7, s6, 31
	s_bfe_i64 s[18:19], s[0:1], 0x100000
	v_or3_b32 v6, v6, v7, v8
	v_lshlrev_b32_e32 v7, 5, v15
	v_ashrrev_i16_sdwa v2, v4, sext(v2) dst_sel:DWORD dst_unused:UNUSED_PAD src0_sel:DWORD src1_sel:BYTE_0
	s_lshl_b64 s[2:3], s[6:7], 20
	s_lshl_b64 s[18:19], s[18:19], 20
	v_readlane_b32 s20, v240, 23
	v_and_b32_e32 v7, 32, v7
	v_bfe_i32 v16, v2, 0, 16
	v_readlane_b32 s21, v240, 24
	s_add_u32 s28, s20, s18
	v_add_lshl_u32 v2, v7, v16, 1
	s_addc_u32 s29, s21, s19
	s_add_i32 s36, s33, 0
	v_lshl_add_u32 v152, v6, 12, v2
	s_add_i32 m0, s36, 0x10000
	v_lshl_add_u32 v154, v5, 12, v2
	global_load_lds_dwordx4 v152, s[28:29]
	s_add_i32 m0, s36, 0x12000
	s_add_u32 s18, s28, 0x80000
	global_load_lds_dwordx4 v148, s[28:29]
	s_addc_u32 s19, s29, 0
	s_add_i32 m0, s36, 0x14000
	v_mov_b32_e32 v153, 0
	global_load_lds_dwordx4 v152, s[18:19]
	s_add_i32 m0, s36, 0x16000
	s_add_u32 s26, s52, s2
	s_addc_u32 s27, s53, s3
	s_add_i32 s37, s36, 0x2000
	global_load_lds_dwordx4 v148, s[18:19]
	s_mov_b32 m0, s36
	s_add_u32 s2, s26, 0x80000
	global_load_lds_dwordx4 v154, s[26:27]
	s_mov_b32 m0, s37
	s_addc_u32 s3, s27, 0
	s_add_i32 s38, s36, 0x4000
	global_load_lds_dwordx4 v150, s[26:27]
	s_mov_b32 m0, s38
	s_add_i32 s39, s36, 0x6000
	global_load_lds_dwordx4 v154, s[2:3]
	s_mov_b32 m0, s39
	v_mov_b32_e32 v149, v153
	global_load_lds_dwordx4 v150, s[2:3]
	v_mov_b32_e32 v155, v153
	v_mov_b32_e32 v151, v153
	s_cmp_eq_u32 s16, 1
	s_mov_b32 s40, 0
	v_lshl_add_u64 v[8:9], s[28:29], 0, v[152:153]
	v_lshl_add_u64 v[6:7], s[28:29], 0, v[148:149]
	v_lshl_add_u64 v[2:3], s[26:27], 0, v[154:155]
	s_cselect_b64 s[2:3], -1, 0
	s_cmp_lg_u32 s16, 1
	v_lshl_add_u64 v[4:5], s[26:27], 0, v[150:151]
	s_cbranch_scc1 .LBB0_1202
	s_barrier
